# up2 chunk-gating item: row statistics loads issued together (one round trip instead of four)
# baseline (speedup 1.0000x reference)
.LBB0_482:
	s_and_b32 s15, s11, 0xffffff80
	s_and_saveexec_b64 s[8:9], vcc
	s_cbranch_execz .LBB0_485
	v_add_u32_e32 v0, s15, v56
	v_ashrrev_i32_e32 v1, 31, v0
	v_lshlrev_b64 v[0:1], 10, v[0:1]
	v_lshl_add_u64 v[16:17], v[46:47], 0, v[0:1]
	global_load_dwordx4 v[0:3], v[16:17], off offset:560
	global_load_dwordx4 v[4:7], v[16:17], off offset:544
	global_load_dwordx4 v[8:11], v[16:17], off offset:528
	global_load_dwordx4 v[12:15], v[16:17], off offset:512
	global_load_dwordx4 v[102:105], v[16:17], off offset:624
	global_load_dwordx4 v[106:109], v[16:17], off offset:608
	global_load_dwordx4 v[110:113], v[16:17], off offset:592
	global_load_dwordx4 v[114:117], v[16:17], off offset:576
	global_load_dwordx4 v[118:121], v[16:17], off offset:688
	global_load_dwordx4 v[122:125], v[16:17], off offset:672
	global_load_dwordx4 v[126:129], v[16:17], off offset:656
	global_load_dwordx4 v[130:133], v[16:17], off offset:640
	global_load_dwordx4 v[134:137], v[16:17], off offset:752
	global_load_dwordx4 v[138:141], v[16:17], off offset:736
	global_load_dwordx4 v[142:145], v[16:17], off offset:720
	global_load_dwordx4 v[146:149], v[16:17], off offset:704
	s_waitcnt vmcnt(0)
	v_lshlrev_b32_e32 v83, 16, v4
	v_lshlrev_b32_e32 v33, 16, v8
	v_and_b32_e32 v21, 0xffff0000, v13
	v_lshlrev_b32_e32 v13, 16, v13
	v_and_b32_e32 v19, 0xffff0000, v12
	v_lshlrev_b32_e32 v12, 16, v12
	v_mov_b32_e32 v18, v13
	v_pk_mul_f32 v[24:25], v[12:13], v[18:19] op_sel:[1,0] op_sel_hi:[0,1]
	v_pk_add_f32 v[26:27], v[12:13], v[18:19] op_sel:[1,0] op_sel_hi:[0,1]
	v_mul_f32_e32 v22, v12, v12
	v_mov_b32_e32 v25, v27
	v_mul_f32_e32 v176, v21, v21
	v_lshlrev_b32_e32 v27, 16, v14
	v_and_b32_e32 v29, 0xffff0000, v14
	v_mov_b32_e32 v23, v13
	v_mul_f32_e32 v20, v19, v19
	v_mul_f32_e32 v26, v27, v27
	v_mul_f32_e32 v28, v29, v29
	v_lshlrev_b32_e32 v31, 16, v15
	v_and_b32_e32 v15, 0xffff0000, v15
	v_pk_add_f32 v[12:13], v[22:23], v[20:21]
	v_pk_add_f32 v[18:19], v[24:25], v[176:177]
	v_mul_f32_e32 v30, v31, v31
	v_mul_f32_e32 v14, v15, v15
	v_and_b32_e32 v35, 0xffff0000, v8
	v_pk_add_f32 v[12:13], v[12:13], v[18:19]
	v_pk_add_f32 v[18:19], v[26:27], v[28:29]
	v_mul_f32_e32 v32, v33, v33
	v_mul_f32_e32 v34, v35, v35
	v_lshlrev_b32_e32 v51, 16, v9
	v_and_b32_e32 v9, 0xffff0000, v9
	v_pk_add_f32 v[12:13], v[18:19], v[12:13]
	v_pk_add_f32 v[14:15], v[30:31], v[14:15]
	v_mul_f32_e32 v50, v51, v51
	v_mul_f32_e32 v8, v9, v9
	v_lshlrev_b32_e32 v53, 16, v10
	v_and_b32_e32 v55, 0xffff0000, v10
	v_pk_add_f32 v[12:13], v[14:15], v[12:13]
	v_pk_add_f32 v[14:15], v[32:33], v[34:35]
	v_mul_f32_e32 v52, v53, v53
	v_mul_f32_e32 v54, v55, v55
	v_lshlrev_b32_e32 v81, 16, v11
	v_and_b32_e32 v11, 0xffff0000, v11
	v_pk_add_f32 v[12:13], v[14:15], v[12:13]
	v_pk_add_f32 v[8:9], v[50:51], v[8:9]
	v_mul_f32_e32 v80, v81, v81
	v_mul_f32_e32 v10, v11, v11
	v_and_b32_e32 v85, 0xffff0000, v4
	v_pk_add_f32 v[8:9], v[8:9], v[12:13]
	v_pk_add_f32 v[12:13], v[52:53], v[54:55]
	v_mul_f32_e32 v82, v83, v83
	v_mul_f32_e32 v84, v85, v85
	v_lshlrev_b32_e32 v87, 16, v5
	v_and_b32_e32 v5, 0xffff0000, v5
	v_pk_add_f32 v[8:9], v[12:13], v[8:9]
	v_pk_add_f32 v[10:11], v[80:81], v[10:11]
	v_mul_f32_e32 v86, v87, v87
	v_mul_f32_e32 v4, v5, v5
	v_pk_add_f32 v[8:9], v[10:11], v[8:9]
	v_pk_add_f32 v[10:11], v[82:83], v[84:85]
	v_pk_add_f32 v[4:5], v[86:87], v[4:5]
	v_pk_add_f32 v[8:9], v[10:11], v[8:9]
	v_lshlrev_b32_e32 v51, 16, v7
	v_pk_add_f32 v[32:33], v[4:5], v[8:9]
	v_lshlrev_b32_e32 v5, 16, v6
	v_and_b32_e32 v9, 0xffff0000, v6
	v_mul_f32_e32 v4, v5, v5
	v_mul_f32_e32 v8, v9, v9
	v_pk_add_f32 v[54:55], v[4:5], v[8:9]
	v_and_b32_e32 v53, 0xffff0000, v7
	v_lshlrev_b32_e32 v31, 16, v0
	v_and_b32_e32 v35, 0xffff0000, v0
	v_lshlrev_b32_e32 v27, 16, v1
	v_and_b32_e32 v29, 0xffff0000, v1
	v_lshlrev_b32_e32 v23, 16, v2
	v_and_b32_e32 v25, 0xffff0000, v2
	v_lshlrev_b32_e32 v19, 16, v3
	v_and_b32_e32 v21, 0xffff0000, v3
	v_mul_f32_e32 v50, v51, v51
	v_mul_f32_e32 v52, v53, v53
	v_mul_f32_e32 v30, v31, v31
	v_mul_f32_e32 v34, v35, v35
	v_pk_add_f32 v[32:33], v[54:55], v[32:33]
	v_pk_add_f32 v[50:51], v[50:51], v[52:53]
	v_mul_f32_e32 v26, v27, v27
	v_mul_f32_e32 v28, v29, v29
	v_pk_add_f32 v[32:33], v[50:51], v[32:33]
	v_pk_add_f32 v[30:31], v[30:31], v[34:35]
	v_mul_f32_e32 v22, v23, v23
	v_mul_f32_e32 v24, v25, v25
	v_pk_add_f32 v[30:31], v[30:31], v[32:33]
	v_pk_add_f32 v[26:27], v[26:27], v[28:29]
	v_mul_f32_e32 v18, v19, v19
	v_mul_f32_e32 v20, v21, v21
	v_pk_add_f32 v[26:27], v[26:27], v[30:31]
	v_pk_add_f32 v[22:23], v[22:23], v[24:25]
	v_pk_add_f32 v[18:19], v[18:19], v[20:21]
	v_pk_add_f32 v[22:23], v[22:23], v[26:27]
	v_lshlrev_b32_e32 v35, 16, v102
	v_pk_add_f32 v[18:19], v[18:19], v[22:23]
	v_lshlrev_b32_e32 v93, 16, v110
	v_lshlrev_b32_e32 v81, 16, v114
	v_and_b32_e32 v83, 0xffff0000, v114
	v_mul_f32_e32 v80, v81, v81
	v_mul_f32_e32 v82, v83, v83
	v_lshlrev_b32_e32 v85, 16, v115
	v_and_b32_e32 v115, 0xffff0000, v115
	v_mul_f32_e32 v84, v85, v85
	v_mul_f32_e32 v114, v115, v115
	v_lshlrev_b32_e32 v87, 16, v116
	v_and_b32_e32 v89, 0xffff0000, v116
	v_pk_add_f32 v[20:21], v[80:81], v[82:83]
	v_mul_f32_e32 v86, v87, v87
	v_mul_f32_e32 v88, v89, v89
	v_lshlrev_b32_e32 v91, 16, v117
	v_and_b32_e32 v117, 0xffff0000, v117
	v_pk_add_f32 v[18:19], v[20:21], v[18:19]
	v_pk_add_f32 v[114:115], v[84:85], v[114:115]
	v_mul_f32_e32 v90, v91, v91
	v_mul_f32_e32 v116, v117, v117
	v_and_b32_e32 v95, 0xffff0000, v110
	v_pk_add_f32 v[114:115], v[114:115], v[18:19]
	v_pk_add_f32 v[18:19], v[86:87], v[88:89]
	v_mul_f32_e32 v92, v93, v93
	v_mul_f32_e32 v94, v95, v95
	v_pk_add_f32 v[114:115], v[18:19], v[114:115]
	v_pk_add_f32 v[116:117], v[90:91], v[116:117]
	v_and_b32_e32 v19, 0xffff0000, v112
	v_pk_add_f32 v[114:115], v[116:117], v[114:115]
	v_pk_add_f32 v[116:117], v[92:93], v[94:95]
	v_mul_f32_e32 v18, v19, v19
	v_pk_add_f32 v[114:115], v[116:117], v[114:115]
	v_lshlrev_b32_e32 v117, 16, v111
	v_and_b32_e32 v111, 0xffff0000, v111
	v_mul_f32_e32 v116, v117, v117
	v_mul_f32_e32 v110, v111, v111
	v_pk_add_f32 v[110:111], v[116:117], v[110:111]
	v_lshlrev_b32_e32 v117, 16, v112
	v_mul_f32_e32 v116, v117, v117
	v_lshlrev_b32_e32 v21, 16, v113
	v_and_b32_e32 v113, 0xffff0000, v113
	v_mul_f32_e32 v20, v21, v21
	v_mul_f32_e32 v112, v113, v113
	v_lshlrev_b32_e32 v23, 16, v106
	v_and_b32_e32 v25, 0xffff0000, v106
	v_pk_add_f32 v[110:111], v[110:111], v[114:115]
	v_pk_add_f32 v[114:115], v[116:117], v[18:19]
	v_mul_f32_e32 v22, v23, v23
	v_mul_f32_e32 v24, v25, v25
	v_lshlrev_b32_e32 v27, 16, v107
	v_and_b32_e32 v107, 0xffff0000, v107
	v_pk_add_f32 v[110:111], v[114:115], v[110:111]
	v_pk_add_f32 v[112:113], v[20:21], v[112:113]
	v_mul_f32_e32 v26, v27, v27
	v_mul_f32_e32 v106, v107, v107
	v_lshlrev_b32_e32 v29, 16, v108
	v_and_b32_e32 v31, 0xffff0000, v108
	v_pk_add_f32 v[110:111], v[112:113], v[110:111]
	v_pk_add_f32 v[112:113], v[22:23], v[24:25]
	v_mul_f32_e32 v28, v29, v29
	v_mul_f32_e32 v30, v31, v31
	v_lshlrev_b32_e32 v33, 16, v109
	v_and_b32_e32 v109, 0xffff0000, v109
	v_pk_add_f32 v[110:111], v[112:113], v[110:111]
	v_pk_add_f32 v[106:107], v[26:27], v[106:107]
	v_mul_f32_e32 v32, v33, v33
	v_mul_f32_e32 v108, v109, v109
	v_and_b32_e32 v51, 0xffff0000, v102
	v_pk_add_f32 v[106:107], v[106:107], v[110:111]
	v_pk_add_f32 v[110:111], v[28:29], v[30:31]
	v_mul_f32_e32 v34, v35, v35
	v_mul_f32_e32 v50, v51, v51
	v_lshlrev_b32_e32 v53, 16, v103
	v_and_b32_e32 v103, 0xffff0000, v103
	v_pk_add_f32 v[106:107], v[110:111], v[106:107]
	v_pk_add_f32 v[108:109], v[32:33], v[108:109]
	v_mul_f32_e32 v52, v53, v53
	v_mul_f32_e32 v102, v103, v103
	v_lshlrev_b32_e32 v55, 16, v104
	v_and_b32_e32 v81, 0xffff0000, v104
	v_pk_add_f32 v[106:107], v[108:109], v[106:107]
	v_pk_add_f32 v[108:109], v[34:35], v[50:51]
	v_mul_f32_e32 v54, v55, v55
	v_mul_f32_e32 v80, v81, v81
	v_lshlrev_b32_e32 v83, 16, v105
	v_and_b32_e32 v105, 0xffff0000, v105
	v_pk_add_f32 v[106:107], v[108:109], v[106:107]
	v_pk_add_f32 v[102:103], v[52:53], v[102:103]
	v_mul_f32_e32 v82, v83, v83
	v_mul_f32_e32 v104, v105, v105
	v_pk_add_f32 v[102:103], v[102:103], v[106:107]
	v_pk_add_f32 v[106:107], v[54:55], v[80:81]
	v_pk_add_f32 v[104:105], v[82:83], v[104:105]
	v_pk_add_f32 v[102:103], v[106:107], v[102:103]
	s_nop 0
	v_pk_add_f32 v[18:19], v[104:105], v[102:103]
	v_lshlrev_b32_e32 v81, 16, v122
	v_lshlrev_b32_e32 v31, 16, v126
	v_lshlrev_b32_e32 v21, 16, v130
	v_and_b32_e32 v23, 0xffff0000, v130
	v_mul_f32_e32 v20, v21, v21
	v_mul_f32_e32 v22, v23, v23
	v_pk_add_f32 v[20:21], v[20:21], v[22:23]
	v_lshlrev_b32_e32 v23, 16, v131
	v_and_b32_e32 v131, 0xffff0000, v131
	v_mul_f32_e32 v22, v23, v23
	v_mul_f32_e32 v130, v131, v131
	v_lshlrev_b32_e32 v25, 16, v132
	v_and_b32_e32 v27, 0xffff0000, v132
	v_mul_f32_e32 v24, v25, v25
	v_mul_f32_e32 v26, v27, v27
	v_lshlrev_b32_e32 v29, 16, v133
	v_and_b32_e32 v133, 0xffff0000, v133
	v_pk_add_f32 v[18:19], v[20:21], v[18:19]
	v_pk_add_f32 v[130:131], v[22:23], v[130:131]
	v_mul_f32_e32 v28, v29, v29
	v_mul_f32_e32 v132, v133, v133
	v_and_b32_e32 v33, 0xffff0000, v126
	v_pk_add_f32 v[130:131], v[130:131], v[18:19]
	v_pk_add_f32 v[18:19], v[24:25], v[26:27]
	v_mul_f32_e32 v30, v31, v31
	v_mul_f32_e32 v32, v33, v33
	v_lshlrev_b32_e32 v35, 16, v127
	v_and_b32_e32 v127, 0xffff0000, v127
	v_pk_add_f32 v[130:131], v[18:19], v[130:131]
	v_pk_add_f32 v[132:133], v[28:29], v[132:133]
	v_mul_f32_e32 v34, v35, v35
	v_mul_f32_e32 v126, v127, v127
	v_lshlrev_b32_e32 v51, 16, v128
	v_and_b32_e32 v53, 0xffff0000, v128
	v_pk_add_f32 v[130:131], v[132:133], v[130:131]
	v_pk_add_f32 v[132:133], v[30:31], v[32:33]
	v_mul_f32_e32 v50, v51, v51
	v_mul_f32_e32 v52, v53, v53
	v_lshlrev_b32_e32 v55, 16, v129
	v_and_b32_e32 v129, 0xffff0000, v129
	v_pk_add_f32 v[130:131], v[132:133], v[130:131]
	v_pk_add_f32 v[126:127], v[34:35], v[126:127]
	v_mul_f32_e32 v54, v55, v55
	v_mul_f32_e32 v128, v129, v129
	v_and_b32_e32 v83, 0xffff0000, v122
	v_pk_add_f32 v[126:127], v[126:127], v[130:131]
	v_pk_add_f32 v[130:131], v[50:51], v[52:53]
	v_mul_f32_e32 v80, v81, v81
	v_mul_f32_e32 v82, v83, v83
	v_lshlrev_b32_e32 v85, 16, v123
	v_and_b32_e32 v123, 0xffff0000, v123
	v_pk_add_f32 v[126:127], v[130:131], v[126:127]
	v_pk_add_f32 v[128:129], v[54:55], v[128:129]
	v_mul_f32_e32 v84, v85, v85
	v_mul_f32_e32 v122, v123, v123
	v_lshlrev_b32_e32 v87, 16, v124
	v_and_b32_e32 v89, 0xffff0000, v124
	v_pk_add_f32 v[126:127], v[128:129], v[126:127]
	v_pk_add_f32 v[128:129], v[80:81], v[82:83]
	v_mul_f32_e32 v86, v87, v87
	v_mul_f32_e32 v88, v89, v89
	v_pk_add_f32 v[126:127], v[128:129], v[126:127]
	v_pk_add_f32 v[122:123], v[84:85], v[122:123]
	v_lshlrev_b32_e32 v33, 16, v118
	v_pk_add_f32 v[122:123], v[122:123], v[126:127]
	v_pk_add_f32 v[126:127], v[86:87], v[88:89]
	v_and_b32_e32 v35, 0xffff0000, v118
	v_pk_add_f32 v[28:29], v[126:127], v[122:123]
	v_lshlrev_b32_e32 v123, 16, v125
	v_and_b32_e32 v125, 0xffff0000, v125
	v_mul_f32_e32 v122, v123, v123
	v_mul_f32_e32 v124, v125, v125
	v_pk_add_f32 v[50:51], v[122:123], v[124:125]
	v_lshlrev_b32_e32 v27, 16, v119
	v_and_b32_e32 v31, 0xffff0000, v119
	v_lshlrev_b32_e32 v23, 16, v120
	v_and_b32_e32 v25, 0xffff0000, v120
	v_lshlrev_b32_e32 v19, 16, v121
	v_and_b32_e32 v21, 0xffff0000, v121
	v_mul_f32_e32 v32, v33, v33
	v_mul_f32_e32 v34, v35, v35
	v_mul_f32_e32 v26, v27, v27
	v_mul_f32_e32 v30, v31, v31
	v_pk_add_f32 v[28:29], v[50:51], v[28:29]
	v_pk_add_f32 v[32:33], v[32:33], v[34:35]
	v_mul_f32_e32 v22, v23, v23
	v_mul_f32_e32 v24, v25, v25
	v_pk_add_f32 v[28:29], v[32:33], v[28:29]
	v_pk_add_f32 v[26:27], v[26:27], v[30:31]
	v_mul_f32_e32 v18, v19, v19
	v_mul_f32_e32 v20, v21, v21
	v_pk_add_f32 v[26:27], v[26:27], v[28:29]
	v_pk_add_f32 v[22:23], v[22:23], v[24:25]
	v_pk_add_f32 v[18:19], v[18:19], v[20:21]
	v_pk_add_f32 v[22:23], v[22:23], v[26:27]
	v_lshlrev_b32_e32 v29, 16, v134
	v_pk_add_f32 v[18:19], v[18:19], v[22:23]
	v_lshlrev_b32_e32 v87, 16, v142
	v_lshlrev_b32_e32 v17, 16, v146
	v_and_b32_e32 v53, 0xffff0000, v146
	v_mul_f32_e32 v16, v17, v17
	v_mul_f32_e32 v52, v53, v53
	v_lshlrev_b32_e32 v55, 16, v147
	v_and_b32_e32 v147, 0xffff0000, v147
	v_mul_f32_e32 v54, v55, v55
	v_mul_f32_e32 v146, v147, v147
	v_lshlrev_b32_e32 v81, 16, v148
	v_and_b32_e32 v83, 0xffff0000, v148
	v_pk_add_f32 v[16:17], v[16:17], v[52:53]
	v_mul_f32_e32 v80, v81, v81
	v_mul_f32_e32 v82, v83, v83
	v_lshlrev_b32_e32 v85, 16, v149
	v_and_b32_e32 v149, 0xffff0000, v149
	v_pk_add_f32 v[16:17], v[16:17], v[18:19]
	v_pk_add_f32 v[146:147], v[54:55], v[146:147]
	v_mul_f32_e32 v84, v85, v85
	v_mul_f32_e32 v148, v149, v149
	v_and_b32_e32 v89, 0xffff0000, v142
	v_pk_add_f32 v[146:147], v[146:147], v[16:17]
	v_pk_add_f32 v[16:17], v[80:81], v[82:83]
	v_mul_f32_e32 v86, v87, v87
	v_mul_f32_e32 v88, v89, v89
	v_lshlrev_b32_e32 v91, 16, v143
	v_and_b32_e32 v143, 0xffff0000, v143
	v_pk_add_f32 v[146:147], v[16:17], v[146:147]
	v_pk_add_f32 v[148:149], v[84:85], v[148:149]
	v_mul_f32_e32 v90, v91, v91
	v_mul_f32_e32 v142, v143, v143
	v_pk_add_f32 v[146:147], v[148:149], v[146:147]
	v_pk_add_f32 v[148:149], v[86:87], v[88:89]
	v_pk_add_f32 v[142:143], v[90:91], v[142:143]
	v_pk_add_f32 v[146:147], v[148:149], v[146:147]
	v_and_b32_e32 v149, 0xffff0000, v144
	v_pk_add_f32 v[142:143], v[142:143], v[146:147]
	v_lshlrev_b32_e32 v147, 16, v144
	v_mul_f32_e32 v146, v147, v147
	v_mul_f32_e32 v148, v149, v149
	v_pk_add_f32 v[146:147], v[146:147], v[148:149]
	v_lshlrev_b32_e32 v149, 16, v145
	v_and_b32_e32 v145, 0xffff0000, v145
	v_mul_f32_e32 v148, v149, v149
	v_mul_f32_e32 v144, v145, v145
	v_lshlrev_b32_e32 v17, 16, v138
	v_and_b32_e32 v19, 0xffff0000, v138
	v_mul_f32_e32 v16, v17, v17
	v_mul_f32_e32 v18, v19, v19
	v_lshlrev_b32_e32 v21, 16, v139
	v_and_b32_e32 v139, 0xffff0000, v139
	v_pk_add_f32 v[142:143], v[146:147], v[142:143]
	v_pk_add_f32 v[144:145], v[148:149], v[144:145]
	v_mul_f32_e32 v20, v21, v21
	v_mul_f32_e32 v138, v139, v139
	v_lshlrev_b32_e32 v23, 16, v140
	v_and_b32_e32 v25, 0xffff0000, v140
	v_pk_add_f32 v[142:143], v[144:145], v[142:143]
	v_pk_add_f32 v[144:145], v[16:17], v[18:19]
	v_mul_f32_e32 v22, v23, v23
	v_mul_f32_e32 v24, v25, v25
	v_lshlrev_b32_e32 v27, 16, v141
	v_and_b32_e32 v141, 0xffff0000, v141
	v_pk_add_f32 v[142:143], v[144:145], v[142:143]
	v_pk_add_f32 v[138:139], v[20:21], v[138:139]
	v_mul_f32_e32 v26, v27, v27
	v_mul_f32_e32 v140, v141, v141
	v_and_b32_e32 v31, 0xffff0000, v134
	v_pk_add_f32 v[138:139], v[138:139], v[142:143]
	v_pk_add_f32 v[142:143], v[22:23], v[24:25]
	v_mul_f32_e32 v28, v29, v29
	v_mul_f32_e32 v30, v31, v31
	v_lshlrev_b32_e32 v33, 16, v135
	v_and_b32_e32 v135, 0xffff0000, v135
	v_pk_add_f32 v[138:139], v[142:143], v[138:139]
	v_pk_add_f32 v[140:141], v[26:27], v[140:141]
	v_mul_f32_e32 v32, v33, v33
	v_mul_f32_e32 v134, v135, v135
	v_lshlrev_b32_e32 v35, 16, v136
	v_and_b32_e32 v51, 0xffff0000, v136
	v_pk_add_f32 v[138:139], v[140:141], v[138:139]
	v_pk_add_f32 v[140:141], v[28:29], v[30:31]
	v_mul_f32_e32 v34, v35, v35
	v_mul_f32_e32 v50, v51, v51
	v_lshlrev_b32_e32 v53, 16, v137
	v_and_b32_e32 v137, 0xffff0000, v137
	v_pk_add_f32 v[138:139], v[140:141], v[138:139]
	v_pk_add_f32 v[134:135], v[32:33], v[134:135]
	v_mul_f32_e32 v52, v53, v53
	v_mul_f32_e32 v136, v137, v137
	v_pk_add_f32 v[134:135], v[134:135], v[138:139]
	v_pk_add_f32 v[138:139], v[34:35], v[50:51]
	v_pk_add_f32 v[136:137], v[52:53], v[136:137]
	v_pk_add_f32 v[134:135], v[138:139], v[134:135]
	s_nop 0
	v_pk_add_f32 v[134:135], v[136:137], v[134:135]
	v_and_b32_e32 v137, 64, v196
	v_xor_b32_e32 v136, 1, v196
	v_add_u32_e32 v137, 64, v137
	v_cmp_lt_i32_e64 s[6:7], v136, v137
	s_nop 1
	v_cndmask_b32_e64 v136, v196, v136, s[6:7]
	v_lshlrev_b32_e32 v136, 2, v136
	v_mov_b32_e32 v0, v134
	v_mov_b32_e32 v1, v135
	v_mov_b32_e32 v2, v136
	v_mov_b32_e32 v3, v137
	v_mov_b32_e32 v4, v138
	v_mov_b32_e32 v5, v139
	v_mov_b32_e32 v6, v140
	v_mov_b32_e32 v7, v141
	v_mov_b32_e32 v8, v142
	v_mov_b32_e32 v9, v143
	v_mov_b32_e32 v10, v144
	v_mov_b32_e32 v11, v145
	v_mov_b32_e32 v12, v146
	v_mov_b32_e32 v13, v147
	v_mov_b32_e32 v14, v148
	v_mov_b32_e32 v15, v149
	ds_bpermute_b32 v3, v2, v1
	ds_bpermute_b32 v2, v2, v0
	s_and_b64 exec, exec, s[2:3]
	s_cbranch_execz .LBB0_485
	s_waitcnt lgkmcnt(0)
	v_pk_add_f32 v[0:1], v[0:1], v[2:3]
	s_mov_b32 s6, 0x3b800000
	v_pk_mul_f32 v[0:1], v[0:1], s[6:7] op_sel_hi:[1,0]
	s_mov_b32 s6, 0x800000
	v_fma_f32 v0, -v1, v1, v0
	v_max_f32_e32 v0, 0, v0
	v_add_f32_e32 v0, 0x358637bd, v0
	v_mul_f32_e32 v2, 0x4b800000, v0
	v_cmp_gt_f32_e64 s[6:7], s6, v0
	s_nop 1
	v_cndmask_b32_e64 v0, v0, v2, s[6:7]
	v_rsq_f32_e32 v0, v0
	s_nop 0
	v_mul_f32_e32 v2, 0x45800000, v0
	v_cndmask_b32_e64 v0, v0, v2, s[6:7]
	ds_write2_b32 v57, v1, v0 offset1:1
